# gate-up next-tile test scalarised: 32-bit s_mul/s_cmp/s_cselect instead of 64-bit multiply chain + v_mov_b64 + v_cmp_lt_i64 in load segment 2
# baseline (speedup 1.0000x reference)
; #define PG8_STAGE(bufoff, gbase, voff) do { _Pragma("unroll") for (int _i = 0; _i < 2; ++_i) { \
;         const unsigned _m0 = ldsb + (unsigned)((bufoff) + _i * 8192); const char* _gb = (const char*)(gbase); \
;         asm volatile("s_mov_b32 m0, %0\n\ts_nop 0\n\tglobal_load_lds_dwordx4 %1, %2" :: "s"(_m0), "v"((voff)[_i]), "s"(_gb) : "m0", "memory"); } } while (0)
; #define PG8_LDA(dst, b, h) do { _Pragma("unroll") for (int m = 0; m < 4; ++m) _Pragma("unroll") for (int k = 0; k < 2; ++k) dst[m][k] = *(const LAS bf16x8*)(lds + PG8_SA(b, h) + aoff + m * 2048 + k * 1024); } while (0)
; #define PG8_LDB(dst, b, h) do { _Pragma("unroll") for (int n = 0; n < 2; ++n) _Pragma("unroll") for (int k = 0; k < 2; ++k) dst[n][k] = *(const LAS bf16x8*)(lds + PG8_SB(b, h) + boff + n * 2048 + k * 1024); } while (0)
; #define PG8_MMA(ai, bj, At, Bt) do { __builtin_amdgcn_s_setprio(1); _Pragma("unroll") for (int m = 0; m < 4; ++m) _Pragma("unroll") for (int n = 0; n < 2; ++n) _Pragma("unroll") for (int k = 0; k < 2; ++k) \
;         acc[ai][bj][m][n] = __builtin_amdgcn_mfma_f32_16x16x32_bf16(Bt[n][k], At[m][k], acc[ai][bj][m][n], 0, 0, 0); __builtin_amdgcn_s_setprio(0); } while (0)
;     __device__ bool next(int i, Unit& u) const {
;         const long L = (long)i * G + c; if (L >= nwg) return false;
; template <class Epi, bool ALIGN_EPI>
; __device__ __forceinline__ void gemm_phase(LAS unsigned char* lds, const Gemm g, const StaticOrder& S, const Epi& E) {
;     ...
;         const bool has_next = S.next(ui + 1, nxt);
;         const char* nA = has_next ? (const char*)g.A + (size_t)nxt.pm * tstepA + (size_t)nxt.pn * g.a_pn_off * 2 + (size_t)(nxt.pm >> 4) * g.a_adj : cA; const char* nB = has_next ? (const char*)g.Bt + (size_t)nxt.pn * tstepB : cB;
;         for (int t = 0; t < nt; t += 2) {
;             const bool last = (t == nt - 2);
;             const char* a1 = cA + (size_t)(t + 1) * kstep;
;             const char* a2 = last ? nA : cA + (size_t)(t + 2) * kstep; const char* b2 = last ? nB : cB + (size_t)(t + 2) * kstep;
;             const char* a3 = a2 + kstep; const char* b3 = b2 + kstep;
;             PG8_LDB(B0, 0, 0); PG8_LDB(B1, 0, 1); PG8_SCHED; PG8_LDA(At, 0, 0); PG8_STAGE(PG8_SA(1, 1), a1 + hstepA, voffA);
;             PG8_WAIT_V(8); PG8_WAIT_L(0); PG8_BAR; PG8_MMA(0, 0, At, B0); PG8_MMA(0, 1, At, B1); PG8_BAR; PG8_SCHED;
.LBB0_305:
	s_add_u32 s41, s56, 0x100
	s_addc_u32 s49, s57, 0
	s_add_u32 s92, s58, 0x40080
	s_addc_u32 s93, s59, 0
	s_mov_b32 s50, -2
	s_add_u32 s30, s92, 0xfffc0080
	s_addc_u32 s31, s93, -1
	s_cmp_eq_u32 s50, 12
	s_cselect_b32 s60, s5, s30
	s_cselect_b32 s61, s4, s31
	s_cselect_b32 s58, s37, s41
	s_cselect_b32 s59, s35, s49
	s_add_u32 s56, s60, 0x80
	s_addc_u32 s57, s61, 0
	s_mov_b32 m0, s67
	s_nop 0
	global_load_lds_dwordx4 v0, s[92:93]
	s_nop 0
	s_mov_b32 m0, s65
	s_nop 0
	global_load_lds_dwordx4 v181, s[92:93]
	s_waitcnt vmcnt(8)
	s_waitcnt lgkmcnt(0)
	s_setprio 1
	s_barrier
	v_mfma_f32_16x16x32_bf16 v[142:145], v[74:77], v[162:165], 0
	v_mfma_f32_16x16x32_bf16 v[142:145], v[94:97], v[166:169], v[142:145]
	v_mfma_f32_16x16x32_bf16 v[138:141], v[114:117], v[162:165], 0
	v_mfma_f32_16x16x32_bf16 v[138:141], v[134:137], v[166:169], v[138:141]
	v_mfma_f32_16x16x32_bf16 v[130:133], v[146:149], v[162:165], 0
	v_mfma_f32_16x16x32_bf16 v[130:133], v[150:153], v[166:169], v[130:133]
	v_mfma_f32_16x16x32_bf16 v[126:129], v[154:157], v[162:165], 0
	v_mfma_f32_16x16x32_bf16 v[126:129], v[158:161], v[166:169], v[126:129]
	v_mfma_f32_16x16x32_bf16 v[106:109], v[154:157], v[170:173], 0
	v_mfma_f32_16x16x32_bf16 v[106:109], v[158:161], v[174:177], v[106:109]
	v_mfma_f32_16x16x32_bf16 v[110:113], v[146:149], v[170:173], 0
	v_mfma_f32_16x16x32_bf16 v[110:113], v[150:153], v[174:177], v[110:113]
	v_mfma_f32_16x16x32_bf16 v[118:121], v[114:117], v[170:173], 0
	v_mfma_f32_16x16x32_bf16 v[118:121], v[134:137], v[174:177], v[118:121]
	v_mfma_f32_16x16x32_bf16 v[122:125], v[74:77], v[170:173], 0
	v_mfma_f32_16x16x32_bf16 v[122:125], v[94:97], v[174:177], v[122:125]
	v_mfma_f32_16x16x32_bf16 v[102:105], v[74:77], v[188:191], 0
	v_mfma_f32_16x16x32_bf16 v[102:105], v[94:97], v[202:205], v[102:105]
	v_mfma_f32_16x16x32_bf16 v[98:101], v[114:117], v[188:191], 0
	v_mfma_f32_16x16x32_bf16 v[98:101], v[134:137], v[202:205], v[98:101]
	v_mfma_f32_16x16x32_bf16 v[90:93], v[146:149], v[188:191], 0
	v_mfma_f32_16x16x32_bf16 v[90:93], v[150:153], v[202:205], v[90:93]
	v_mfma_f32_16x16x32_bf16 v[86:89], v[154:157], v[188:191], 0
	v_mfma_f32_16x16x32_bf16 v[86:89], v[158:161], v[202:205], v[86:89]
	v_mfma_f32_16x16x32_bf16 v[66:69], v[154:157], v[206:209], 0
	v_mfma_f32_16x16x32_bf16 v[66:69], v[158:161], v[210:213], v[66:69]
	v_mfma_f32_16x16x32_bf16 v[70:73], v[146:149], v[206:209], 0
	v_mfma_f32_16x16x32_bf16 v[70:73], v[150:153], v[210:213], v[70:73]
	v_mfma_f32_16x16x32_bf16 v[78:81], v[114:117], v[206:209], 0
	v_mfma_f32_16x16x32_bf16 v[78:81], v[134:137], v[210:213], v[78:81]
	v_mfma_f32_16x16x32_bf16 v[82:85], v[74:77], v[206:209], 0
	v_mfma_f32_16x16x32_bf16 v[82:85], v[94:97], v[210:213], v[82:85]
	s_barrier
	s_setprio 0
	v_mbcnt_lo_u32_b32 v178, -1, 0
	v_mbcnt_hi_u32_b32 v178, -1, v178
	s_lshl_b32 s90, s54, 8
	s_add_i32 s90, s90, s89
	s_lshl_b32 s91, s89, 4
	s_add_i32 s91, s91, 0x23000
	v_add_lshl_u32 v178, v178, s90, 4
	s_mov_b32 m0, s91
	s_nop 0
	global_load_lds_dwordx4 v178, s[24:25]
	global_load_lds_dwordx4 v178, s[24:25] offset:2048
	ds_read_b128 v[162:165], v186 offset:16384
	ds_read_b128 v[166:169], v186 offset:17408
	ds_read_b128 v[170:173], v186 offset:18432
	ds_read_b128 v[174:177], v186 offset:19456
	ds_read_b128 v[188:191], v186 offset:20480
	ds_read_b128 v[202:205], v186 offset:21504
	ds_read_b128 v[206:209], v186 offset:22528
	ds_read_b128 v[210:213], v186 offset:23552
	s_mov_b32 m0, s29
	s_nop 0
	global_load_lds_dwordx4 v180, s[58:59]
	s_add_u32 s30, s58, 0x40000
	s_mov_b32 m0, s42
	s_nop 0
	global_load_lds_dwordx4 v182, s[58:59]
	s_addc_u32 s31, s59, 0
	s_mov_b32 m0, s43
	s_nop 0
	global_load_lds_dwordx4 v180, s[30:31]
	s_nop 0
	s_mov_b32 m0, s44
	s_nop 0
	global_load_lds_dwordx4 v182, s[30:31]
	s_nop 0
	s_mov_b32 m0, s15
	s_nop 0
	global_load_lds_dwordx4 v0, s[60:61]
	s_nop 0
	s_mov_b32 m0, s45
	s_nop 0
	global_load_lds_dwordx4 v181, s[60:61]
	s_mul_i32 s4, s85, s87
	s_add_i32 s4, s4, s16
	s_cmp_lt_u32 s4, s46
	s_cselect_b64 s[8:9], -1, 0
	s_ashr_i32 s5, s4, 31
	s_lshr_b32 s5, s5, 29
	s_add_i32 s5, s4, s5
	s_ashr_i32 s90, s5, 3
	s_and_b32 s5, s5, -8
	s_sub_i32 s4, s4, s5
	s_lshr_b32 s5, s4, 31
	s_or_b32 s5, s78, s5
	s_mul_i32 s4, s5, s4
	s_add_i32 s4, s4, s90
	s_abs_i32 s90, s4
	v_readlane_b32 s91, v254, 48
	s_mul_hi_u32 s91, s90, s91
	s_mul_i32 s34, s91, s26
	s_sub_i32 s90, s90, s34
	s_ashr_i32 s5, s4, 31
	s_add_i32 s34, s91, 1
	s_sub_i32 s35, s90, s26
	s_cmp_ge_u32 s90, s26
	s_cselect_b32 s91, s34, s91
	s_cselect_b32 s90, s35, s90
	s_waitcnt vmcnt(8)
	s_waitcnt lgkmcnt(0)
	s_setprio 1
	s_barrier
	v_mfma_f32_16x16x32_bf16 v[62:65], v[74:77], v[162:165], 0
	v_mfma_f32_16x16x32_bf16 v[62:65], v[94:97], v[166:169], v[62:65]
	v_mfma_f32_16x16x32_bf16 v[58:61], v[114:117], v[162:165], 0
	v_mfma_f32_16x16x32_bf16 v[58:61], v[134:137], v[166:169], v[58:61]
	v_mfma_f32_16x16x32_bf16 v[54:57], v[146:149], v[162:165], 0
	v_mfma_f32_16x16x32_bf16 v[54:57], v[150:153], v[166:169], v[54:57]
	v_mfma_f32_16x16x32_bf16 v[50:53], v[154:157], v[162:165], 0
	v_mfma_f32_16x16x32_bf16 v[50:53], v[158:161], v[166:169], v[50:53]
	v_mfma_f32_16x16x32_bf16 v[34:37], v[154:157], v[170:173], 0
	v_mfma_f32_16x16x32_bf16 v[34:37], v[158:161], v[174:177], v[34:37]
	v_mfma_f32_16x16x32_bf16 v[38:41], v[146:149], v[170:173], 0
	v_mfma_f32_16x16x32_bf16 v[38:41], v[150:153], v[174:177], v[38:41]
	v_mfma_f32_16x16x32_bf16 v[42:45], v[114:117], v[170:173], 0
	v_mfma_f32_16x16x32_bf16 v[42:45], v[134:137], v[174:177], v[42:45]
	v_mfma_f32_16x16x32_bf16 v[46:49], v[74:77], v[170:173], 0
	v_mfma_f32_16x16x32_bf16 v[46:49], v[94:97], v[174:177], v[46:49]
	v_mfma_f32_16x16x32_bf16 v[30:33], v[74:77], v[188:191], 0
	v_mfma_f32_16x16x32_bf16 v[30:33], v[94:97], v[202:205], v[30:33]
	v_mfma_f32_16x16x32_bf16 v[26:29], v[114:117], v[188:191], 0
	v_mfma_f32_16x16x32_bf16 v[26:29], v[134:137], v[202:205], v[26:29]
	v_mfma_f32_16x16x32_bf16 v[22:25], v[146:149], v[188:191], 0
	v_mfma_f32_16x16x32_bf16 v[22:25], v[150:153], v[202:205], v[22:25]
	v_mfma_f32_16x16x32_bf16 v[18:21], v[154:157], v[188:191], 0
	v_mfma_f32_16x16x32_bf16 v[18:21], v[158:161], v[202:205], v[18:21]
	v_mfma_f32_16x16x32_bf16 v[2:5], v[154:157], v[206:209], 0
	v_mfma_f32_16x16x32_bf16 v[2:5], v[158:161], v[210:213], v[2:5]
	v_mfma_f32_16x16x32_bf16 v[6:9], v[146:149], v[206:209], 0
	v_mfma_f32_16x16x32_bf16 v[6:9], v[150:153], v[210:213], v[6:9]
	v_mfma_f32_16x16x32_bf16 v[10:13], v[114:117], v[206:209], 0
	v_mfma_f32_16x16x32_bf16 v[10:13], v[134:137], v[210:213], v[10:13]
	v_mfma_f32_16x16x32_bf16 v[14:17], v[74:77], v[206:209], 0
	v_mfma_f32_16x16x32_bf16 v[14:17], v[94:97], v[210:213], v[14:17]
	s_barrier
; #define PG8_STAGE(bufoff, gbase, voff) do { _Pragma("unroll") for (int _i = 0; _i < 2; ++_i) { \
;         const unsigned _m0 = ldsb + (unsigned)((bufoff) + _i * 8192); const char* _gb = (const char*)(gbase); \
;         asm volatile("s_mov_b32 m0, %0\n\ts_nop 0\n\tglobal_load_lds_dwordx4 %1, %2" :: "s"(_m0), "v"((voff)[_i]), "s"(_gb) : "m0", "memory"); } } while (0)
; #define PG8_LDA(dst, b, h) do { _Pragma("unroll") for (int m = 0; m < 4; ++m) _Pragma("unroll") for (int k = 0; k < 2; ++k) dst[m][k] = *(const LAS bf16x8*)(lds + PG8_SA(b, h) + aoff + m * 2048 + k * 1024); } while (0)
; #define PG8_LDB(dst, b, h) do { _Pragma("unroll") for (int n = 0; n < 2; ++n) _Pragma("unroll") for (int k = 0; k < 2; ++k) dst[n][k] = *(const LAS bf16x8*)(lds + PG8_SB(b, h) + boff + n * 2048 + k * 1024); } while (0)
; #define PG8_MMA(ai, bj, At, Bt) do { __builtin_amdgcn_s_setprio(1); _Pragma("unroll") for (int m = 0; m < 4; ++m) _Pragma("unroll") for (int n = 0; n < 2; ++n) _Pragma("unroll") for (int k = 0; k < 2; ++k) \
;         acc[ai][bj][m][n] = __builtin_amdgcn_mfma_f32_16x16x32_bf16(Bt[n][k], At[m][k], acc[ai][bj][m][n], 0, 0, 0); __builtin_amdgcn_s_setprio(0); } while (0)
; #define PG8_WAIT_V(n) asm volatile("s_waitcnt vmcnt(" #n ")" ::: "memory")
; #define PG8_WAIT_L(n) asm volatile("s_waitcnt lgkmcnt(" #n ")" ::: "memory")
;     __device__ bool next(int i, Unit& u) const {
;     ...
;         const int nig = WGM * nN, gid = wgid / nig, fm = gid * WGM, gsz = (nM - fm) < WGM ? (nM - fm) : WGM;
;         u.pm = fm + ((wgid % nig) % gsz); u.pn = (wgid % nig) / gsz; return true;
; template <class Epi, bool ALIGN_EPI>
; __device__ __forceinline__ void gemm_phase(LAS unsigned char* lds, const Gemm g, const StaticOrder& S, const Epi& E) {
;     ...
;             PG8_WAIT_V(8); PG8_WAIT_L(0); PG8_BAR; PG8_MMA(0, 0, At, B0); PG8_MMA(0, 1, At, B1); PG8_BAR; PG8_SCHED;
;             PG8_LDA(At, 0, 1); PG8_STAGE(PG8_SB(0, 0), b2, voffB); PG8_STAGE(PG8_SB(0, 1), b2 + hstepB, voffB); PG8_STAGE(PG8_SA(0, 0), a2, voffA);
;             PG8_WAIT_V(8); PG8_WAIT_L(0); PG8_BAR; PG8_MMA(1, 0, At, B0); PG8_MMA(1, 1, At, B1); PG8_BAR; PG8_SCHED;
;             PG8_LDB(B0, 1, 0); PG8_LDB(B1, 1, 1); PG8_SCHED; PG8_LDA(At, 1, 0); PG8_STAGE(PG8_SA(0, 1), a2 + hstepA, voffA);
;             PG8_WAIT_V(8); PG8_WAIT_L(0); PG8_BAR; PG8_MMA(0, 0, At, B0); PG8_MMA(0, 1, At, B1); PG8_BAR; PG8_SCHED;
	s_setprio 0
	v_add_u32_e32 v134, 0x18000, v185
	v_add_u32_e32 v158, 0x1c000, v185
	ds_read_b128 v[74:77], v134
	ds_read_b128 v[94:97], v134 offset:1024
	ds_read_b128 v[114:117], v134 offset:2048
	ds_read_b128 v[134:137], v134 offset:3072
	ds_read_b128 v[146:149], v158
	ds_read_b128 v[150:153], v158 offset:1024
	ds_read_b128 v[154:157], v158 offset:2048
	ds_read_b128 v[158:161], v158 offset:3072
	ds_read_b128 v[162:165], v186 offset:32768
	ds_read_b128 v[166:169], v186 offset:33792
	ds_read_b128 v[170:173], v186 offset:34816
	ds_read_b128 v[174:177], v186 offset:35840
	ds_read_b128 v[188:191], v186 offset:36864
	ds_read_b128 v[202:205], v186 offset:37888
	ds_read_b128 v[206:209], v186 offset:38912
	ds_read_b128 v[210:213], v186 offset:39936
	s_add_u32 s30, s60, 0x40000
	s_addc_u32 s31, s61, 0
	s_mov_b32 m0, s55
	s_nop 0
	global_load_lds_dwordx4 v0, s[30:31]
	s_nop 0
	s_mov_b32 m0, s88
	s_nop 0
	global_load_lds_dwordx4 v181, s[30:31]
	s_add_i32 s34, s91, 1
	s_cmp_ge_u32 s90, s26
	s_cselect_b32 s90, s34, s91
	s_xor_b32 s90, s90, s5
	s_sub_i32 s5, s90, s5
	s_lshl_b32 s90, s5, 3
	s_sub_i32 s91, 0x80, s90
	s_min_i32 s91, s91, 8
	s_mul_i32 s5, s5, s26
	s_sub_i32 s4, s4, s5
	s_lshr_b32 s34, s4, 3
	s_and_b32 s4, s4, 7
	s_waitcnt vmcnt(8)
	s_waitcnt lgkmcnt(0)
	s_setprio 1
	s_barrier
	v_mfma_f32_16x16x32_bf16 v[142:145], v[74:77], v[162:165], v[142:145]
	v_mfma_f32_16x16x32_bf16 v[142:145], v[94:97], v[166:169], v[142:145]
	v_mfma_f32_16x16x32_bf16 v[138:141], v[114:117], v[162:165], v[138:141]
	v_mfma_f32_16x16x32_bf16 v[138:141], v[134:137], v[166:169], v[138:141]
	v_mfma_f32_16x16x32_bf16 v[130:133], v[146:149], v[162:165], v[130:133]
	v_mfma_f32_16x16x32_bf16 v[130:133], v[150:153], v[166:169], v[130:133]
	v_mfma_f32_16x16x32_bf16 v[126:129], v[154:157], v[162:165], v[126:129]
	v_mfma_f32_16x16x32_bf16 v[126:129], v[158:161], v[166:169], v[126:129]
	v_mfma_f32_16x16x32_bf16 v[106:109], v[154:157], v[170:173], v[106:109]
	v_mfma_f32_16x16x32_bf16 v[106:109], v[158:161], v[174:177], v[106:109]
	v_mfma_f32_16x16x32_bf16 v[110:113], v[146:149], v[170:173], v[110:113]
	v_mfma_f32_16x16x32_bf16 v[110:113], v[150:153], v[174:177], v[110:113]
	v_mfma_f32_16x16x32_bf16 v[118:121], v[114:117], v[170:173], v[118:121]
	v_mfma_f32_16x16x32_bf16 v[118:121], v[134:137], v[174:177], v[118:121]
	v_mfma_f32_16x16x32_bf16 v[122:125], v[74:77], v[170:173], v[122:125]
	v_mfma_f32_16x16x32_bf16 v[122:125], v[94:97], v[174:177], v[122:125]
	v_mfma_f32_16x16x32_bf16 v[102:105], v[74:77], v[188:191], v[102:105]
	v_mfma_f32_16x16x32_bf16 v[102:105], v[94:97], v[202:205], v[102:105]
	v_mfma_f32_16x16x32_bf16 v[98:101], v[114:117], v[188:191], v[98:101]
	v_mfma_f32_16x16x32_bf16 v[98:101], v[134:137], v[202:205], v[98:101]
	v_mfma_f32_16x16x32_bf16 v[90:93], v[146:149], v[188:191], v[90:93]
	v_mfma_f32_16x16x32_bf16 v[90:93], v[150:153], v[202:205], v[90:93]
	v_mfma_f32_16x16x32_bf16 v[86:89], v[154:157], v[188:191], v[86:89]
	v_mfma_f32_16x16x32_bf16 v[86:89], v[158:161], v[202:205], v[86:89]
	v_mfma_f32_16x16x32_bf16 v[66:69], v[154:157], v[206:209], v[66:69]
	v_mfma_f32_16x16x32_bf16 v[66:69], v[158:161], v[210:213], v[66:69]
	v_mfma_f32_16x16x32_bf16 v[70:73], v[146:149], v[206:209], v[70:73]
	v_mfma_f32_16x16x32_bf16 v[70:73], v[150:153], v[210:213], v[70:73]
	v_mfma_f32_16x16x32_bf16 v[78:81], v[114:117], v[206:209], v[78:81]
	v_mfma_f32_16x16x32_bf16 v[78:81], v[134:137], v[210:213], v[78:81]
	v_mfma_f32_16x16x32_bf16 v[82:85], v[74:77], v[206:209], v[82:85]
	v_mfma_f32_16x16x32_bf16 v[82:85], v[94:97], v[210:213], v[82:85]
	s_barrier
; #define PG8_STAGE(bufoff, gbase, voff) do { _Pragma("unroll") for (int _i = 0; _i < 2; ++_i) { \
;         const unsigned _m0 = ldsb + (unsigned)((bufoff) + _i * 8192); const char* _gb = (const char*)(gbase); \
;         asm volatile("s_mov_b32 m0, %0\n\ts_nop 0\n\tglobal_load_lds_dwordx4 %1, %2" :: "s"(_m0), "v"((voff)[_i]), "s"(_gb) : "m0", "memory"); } } while (0)
; #define PG8_LDA(dst, b, h) do { _Pragma("unroll") for (int m = 0; m < 4; ++m) _Pragma("unroll") for (int k = 0; k < 2; ++k) dst[m][k] = *(const LAS bf16x8*)(lds + PG8_SA(b, h) + aoff + m * 2048 + k * 1024); } while (0)
; #define PG8_MMA(ai, bj, At, Bt) do { __builtin_amdgcn_s_setprio(1); _Pragma("unroll") for (int m = 0; m < 4; ++m) _Pragma("unroll") for (int n = 0; n < 2; ++n) _Pragma("unroll") for (int k = 0; k < 2; ++k) \
;         acc[ai][bj][m][n] = __builtin_amdgcn_mfma_f32_16x16x32_bf16(Bt[n][k], At[m][k], acc[ai][bj][m][n], 0, 0, 0); __builtin_amdgcn_s_setprio(0); } while (0)
; #define PG8_WAIT_V(n) asm volatile("s_waitcnt vmcnt(" #n ")" ::: "memory")
; #define PG8_WAIT_L(n) asm volatile("s_waitcnt lgkmcnt(" #n ")" ::: "memory")
; #define PG8_BAR __builtin_amdgcn_s_barrier()
; #define PG8_SCHED __builtin_amdgcn_sched_barrier(0)
; template <class Epi, bool ALIGN_EPI>
; __device__ __forceinline__ void gemm_phase(LAS unsigned char* lds, const Gemm g, const StaticOrder& S, const Epi& E) {
;     ...
;         const char* nA = has_next ? (const char*)g.A + (size_t)nxt.pm * tstepA + (size_t)nxt.pn * g.a_pn_off * 2 + (size_t)(nxt.pm >> 4) * g.a_adj : cA; const char* nB = has_next ? (const char*)g.Bt + (size_t)nxt.pn * tstepB : cB;
;     ...
;             PG8_WAIT_V(8); PG8_WAIT_L(0); PG8_BAR; PG8_MMA(0, 0, At, B0); PG8_MMA(0, 1, At, B1); PG8_BAR; PG8_SCHED;
;             PG8_LDA(At, 1, 1); PG8_STAGE(PG8_SB(1, 0), b3, voffB); PG8_STAGE(PG8_SB(1, 1), b3 + hstepB, voffB); PG8_STAGE(PG8_SA(1, 0), a3, voffA);
;             PG8_WAIT_V(8); PG8_WAIT_L(0); PG8_BAR; PG8_MMA(1, 0, At, B0); PG8_MMA(1, 1, At, B1); PG8_BAR; PG8_SCHED;
	s_setprio 0
	ds_read_b128 v[162:165], v186 offset:49152
	ds_read_b128 v[166:169], v186 offset:50176
	ds_read_b128 v[170:173], v186 offset:51200
	ds_read_b128 v[174:177], v186 offset:52224
	ds_read_b128 v[188:191], v186 offset:53248
	ds_read_b128 v[202:205], v186 offset:54272
	ds_read_b128 v[206:209], v186 offset:55296
	ds_read_b128 v[210:213], v186 offset:56320
	s_add_u32 s30, s58, 0x80
	s_addc_u32 s31, s59, 0
	s_mov_b32 m0, s94
	s_nop 0
	global_load_lds_dwordx4 v180, s[30:31]
	s_nop 0
	s_mov_b32 m0, s95
	s_nop 0
	global_load_lds_dwordx4 v182, s[30:31]
	s_add_u32 s30, s58, 0x40080
	s_addc_u32 s31, s59, 0
	s_mov_b32 m0, s17
	s_nop 0
	global_load_lds_dwordx4 v180, s[30:31]
	s_nop 0
	s_mov_b32 m0, s53
	s_nop 0
	global_load_lds_dwordx4 v182, s[30:31]
	s_nop 0
	s_mov_b32 m0, s96
	s_nop 0
	global_load_lds_dwordx4 v0, s[56:57]
	s_nop 0
	s_mov_b32 m0, s97
	s_nop 0
	global_load_lds_dwordx4 v181, s[56:57]
	s_add_i32 s36, s4, s90
	s_ashr_i32 s37, s36, 31
	s_lshl_b64 s[4:5], s[36:37], 19
	s_add_u32 s38, s18, s4
	s_addc_u32 s39, s19, s5
	s_and_b64 s[4:5], s[8:9], exec
	s_cselect_b32 s4, s39, s59
	s_cselect_b32 s5, s38, s58
	s_ashr_i32 s35, s34, 31
	s_lshl_b64 vcc, s[34:35], 19
	s_add_u32 s90, s1, vcc_lo
	s_addc_u32 s91, s14, vcc_hi
	s_and_b64 vcc, s[8:9], exec
	s_cselect_b32 s35, s91, s57
	s_cselect_b32 s37, s90, s56
	s_waitcnt vmcnt(8)
	s_waitcnt lgkmcnt(0)
	s_setprio 1
	s_barrier
	v_mfma_f32_16x16x32_bf16 v[62:65], v[74:77], v[162:165], v[62:65]
	v_mfma_f32_16x16x32_bf16 v[62:65], v[94:97], v[166:169], v[62:65]
	v_mfma_f32_16x16x32_bf16 v[58:61], v[114:117], v[162:165], v[58:61]
	v_mfma_f32_16x16x32_bf16 v[58:61], v[134:137], v[166:169], v[58:61]
	v_mfma_f32_16x16x32_bf16 v[54:57], v[146:149], v[162:165], v[54:57]
	v_mfma_f32_16x16x32_bf16 v[54:57], v[150:153], v[166:169], v[54:57]
	v_mfma_f32_16x16x32_bf16 v[50:53], v[154:157], v[162:165], v[50:53]
	v_mfma_f32_16x16x32_bf16 v[50:53], v[158:161], v[166:169], v[50:53]
	v_mfma_f32_16x16x32_bf16 v[34:37], v[154:157], v[170:173], v[34:37]
	v_mfma_f32_16x16x32_bf16 v[34:37], v[158:161], v[174:177], v[34:37]
	v_mfma_f32_16x16x32_bf16 v[38:41], v[146:149], v[170:173], v[38:41]
	v_mfma_f32_16x16x32_bf16 v[38:41], v[150:153], v[174:177], v[38:41]
	v_mfma_f32_16x16x32_bf16 v[42:45], v[114:117], v[170:173], v[42:45]
	v_mfma_f32_16x16x32_bf16 v[42:45], v[134:137], v[174:177], v[42:45]
	v_mfma_f32_16x16x32_bf16 v[46:49], v[74:77], v[170:173], v[46:49]
	v_mfma_f32_16x16x32_bf16 v[46:49], v[94:97], v[174:177], v[46:49]
	v_mfma_f32_16x16x32_bf16 v[30:33], v[74:77], v[188:191], v[30:33]
	v_mfma_f32_16x16x32_bf16 v[30:33], v[94:97], v[202:205], v[30:33]
	v_mfma_f32_16x16x32_bf16 v[26:29], v[114:117], v[188:191], v[26:29]
	v_mfma_f32_16x16x32_bf16 v[26:29], v[134:137], v[202:205], v[26:29]
	v_mfma_f32_16x16x32_bf16 v[22:25], v[146:149], v[188:191], v[22:25]
	v_mfma_f32_16x16x32_bf16 v[22:25], v[150:153], v[202:205], v[22:25]
	v_mfma_f32_16x16x32_bf16 v[18:21], v[154:157], v[188:191], v[18:21]
	v_mfma_f32_16x16x32_bf16 v[18:21], v[158:161], v[202:205], v[18:21]
	v_mfma_f32_16x16x32_bf16 v[2:5], v[154:157], v[206:209], v[2:5]
	v_mfma_f32_16x16x32_bf16 v[2:5], v[158:161], v[210:213], v[2:5]
	v_mfma_f32_16x16x32_bf16 v[6:9], v[146:149], v[206:209], v[6:9]
	v_mfma_f32_16x16x32_bf16 v[6:9], v[150:153], v[210:213], v[6:9]
	v_mfma_f32_16x16x32_bf16 v[10:13], v[114:117], v[206:209], v[10:13]
	v_mfma_f32_16x16x32_bf16 v[10:13], v[134:137], v[210:213], v[10:13]
	v_mfma_f32_16x16x32_bf16 v[14:17], v[74:77], v[206:209], v[14:17]
	v_mfma_f32_16x16x32_bf16 v[14:17], v[94:97], v[210:213], v[14:17]
	s_barrier
	s_setprio 0
	s_add_i32 s50, s50, 2
	s_add_u32 s41, s41, 0x100
	s_addc_u32 s49, s49, 0
	s_add_u32 s92, s92, 0x100
	s_addc_u32 s93, s93, 0
	s_cmp_gt_u32 s50, 13
